# GEMM K-loops: removed the momentary setprio 0/1 yield between the two 16-MFMA sub-blocks
# baseline (speedup 1.0000x reference)
.LBB0_169:
	s_add_u32 s26, s34, 0xfffc0080
	s_addc_u32 s27, s35, -1
	s_add_i32 s73, 0, 0x10000
	s_cmp_eq_u32 s72, 12
	s_cselect_b32 s97, s2, s27
	s_cselect_b32 s96, s13, s26
	v_add_u32_e32 v144, s73, v146
	s_cselect_b32 s27, s11, s65
	s_cselect_b32 s26, s25, s63
	s_add_i32 s76, 0, 0x14000
	ds_read_b128 v[150:153], v144
	ds_read_b128 v[154:157], v144 offset:1024
	ds_read_b128 v[158:161], v144 offset:2048
	ds_read_b128 v[162:165], v144 offset:3072
	v_add_u32_e32 v144, s76, v146
	ds_read_b128 v[166:169], v144
	ds_read_b128 v[170:173], v144 offset:1024
	ds_read_b128 v[174:177], v144 offset:2048
	ds_read_b128 v[178:181], v144 offset:3072
	v_lshl_add_u64 v[144:145], s[34:35], 0, v[138:139]
	s_add_i32 m0, s31, 0xc000
	ds_read_b128 v[182:185], v148
	ds_read_b128 v[192:195], v148 offset:1024
	ds_read_b128 v[196:199], v148 offset:2048
	ds_read_b128 v[200:203], v148 offset:3072
	ds_read_b128 v[204:207], v148 offset:4096
	ds_read_b128 v[208:211], v148 offset:5120
	ds_read_b128 v[212:215], v148 offset:6144
	ds_read_b128 v[216:219], v148 offset:7168
	global_load_lds_dwordx4 v[144:145], off
	v_lshl_add_u64 v[144:145], s[34:35], 0, v[140:141]
	s_add_i32 m0, s31, 0xe000
	s_nop 0
	global_load_lds_dwordx4 v[144:145], off
	s_waitcnt vmcnt(8)
	s_waitcnt lgkmcnt(0)
	s_barrier
	s_setprio 1
	s_waitcnt lgkmcnt(0)
	v_mfma_f32_16x16x32_bf16 v[126:129], v[150:153], v[182:185], v[126:129]
	v_mfma_f32_16x16x32_bf16 v[118:121], v[158:161], v[182:185], v[118:121]
	v_mfma_f32_16x16x32_bf16 v[110:113], v[150:153], v[196:199], v[110:113]
	v_mfma_f32_16x16x32_bf16 v[102:105], v[158:161], v[196:199], v[102:105]
	v_mfma_f32_16x16x32_bf16 v[94:97], v[150:153], v[204:207], v[94:97]
	v_mfma_f32_16x16x32_bf16 v[86:89], v[158:161], v[204:207], v[86:89]
	v_mfma_f32_16x16x32_bf16 v[78:81], v[150:153], v[212:215], v[78:81]
	v_mfma_f32_16x16x32_bf16 v[70:73], v[158:161], v[212:215], v[70:73]
	v_mfma_f32_16x16x32_bf16 v[126:129], v[154:157], v[192:195], v[126:129]
	v_mfma_f32_16x16x32_bf16 v[118:121], v[162:165], v[192:195], v[118:121]
	v_mfma_f32_16x16x32_bf16 v[110:113], v[154:157], v[200:203], v[110:113]
	v_mfma_f32_16x16x32_bf16 v[102:105], v[162:165], v[200:203], v[102:105]
	v_mfma_f32_16x16x32_bf16 v[94:97], v[154:157], v[208:211], v[94:97]
	v_mfma_f32_16x16x32_bf16 v[86:89], v[162:165], v[208:211], v[86:89]
	v_mfma_f32_16x16x32_bf16 v[78:81], v[154:157], v[216:219], v[78:81]
	v_mfma_f32_16x16x32_bf16 v[70:73], v[162:165], v[216:219], v[70:73]
	v_mfma_f32_16x16x32_bf16 v[122:125], v[166:169], v[182:185], v[122:125]
	v_mfma_f32_16x16x32_bf16 v[114:117], v[174:177], v[182:185], v[114:117]
	v_mfma_f32_16x16x32_bf16 v[106:109], v[166:169], v[196:199], v[106:109]
	v_mfma_f32_16x16x32_bf16 v[98:101], v[174:177], v[196:199], v[98:101]
	v_mfma_f32_16x16x32_bf16 v[90:93], v[166:169], v[204:207], v[90:93]
	v_mfma_f32_16x16x32_bf16 v[82:85], v[174:177], v[204:207], v[82:85]
	v_mfma_f32_16x16x32_bf16 v[74:77], v[166:169], v[212:215], v[74:77]
	v_mfma_f32_16x16x32_bf16 v[66:69], v[174:177], v[212:215], v[66:69]
	v_mfma_f32_16x16x32_bf16 v[122:125], v[170:173], v[192:195], v[122:125]
	v_mfma_f32_16x16x32_bf16 v[114:117], v[178:181], v[192:195], v[114:117]
	v_mfma_f32_16x16x32_bf16 v[106:109], v[170:173], v[200:203], v[106:109]
	v_mfma_f32_16x16x32_bf16 v[98:101], v[178:181], v[200:203], v[98:101]
	v_mfma_f32_16x16x32_bf16 v[90:93], v[170:173], v[208:211], v[90:93]
	v_mfma_f32_16x16x32_bf16 v[82:85], v[178:181], v[208:211], v[82:85]
	v_mfma_f32_16x16x32_bf16 v[74:77], v[170:173], v[216:219], v[74:77]
	v_mfma_f32_16x16x32_bf16 v[66:69], v[178:181], v[216:219], v[66:69]
	s_setprio 0
	s_barrier
	s_add_i32 s73, s73, s40
	v_lshl_add_u64 v[144:145], s[26:27], 0, v[132:133]
	s_mov_b32 m0, s73
	ds_read_b128 v[182:185], v148 offset:16384
	ds_read_b128 v[192:195], v148 offset:17408
	ds_read_b128 v[196:199], v148 offset:18432
	ds_read_b128 v[200:203], v148 offset:19456
	ds_read_b128 v[204:207], v148 offset:20480
	ds_read_b128 v[208:211], v148 offset:21504
	ds_read_b128 v[212:215], v148 offset:22528
	ds_read_b128 v[216:219], v148 offset:23552
	global_load_lds_dwordx4 v[144:145], off
	s_add_i32 m0, s73, 0x2000
	s_add_u32 s74, s26, 0x40000
	v_lshl_add_u64 v[186:187], s[26:27], 0, v[136:137]
	s_addc_u32 s75, s27, 0
	s_add_i32 s73, s76, s40
	global_load_lds_dwordx4 v[186:187], off
	v_lshl_add_u64 v[220:221], s[74:75], 0, v[132:133]
	s_mov_b32 m0, s73
	v_lshl_add_u64 v[236:237], s[96:97], 0, v[134:135]
	global_load_lds_dwordx4 v[220:221], off
	v_lshl_add_u64 v[220:221], s[74:75], 0, v[136:137]
	s_add_i32 m0, s73, 0x2000
	s_nop 0
	global_load_lds_dwordx4 v[220:221], off
	v_lshl_add_u64 v[220:221], s[96:97], 0, v[130:131]
	s_mov_b32 m0, s31
	s_nop 0
	global_load_lds_dwordx4 v[220:221], off
	s_mov_b32 m0, s41
	s_nop 0
	global_load_lds_dwordx4 v[236:237], off
	s_waitcnt vmcnt(8)
	s_waitcnt lgkmcnt(0)
	s_barrier
	s_setprio 1
	s_waitcnt lgkmcnt(0)
	v_mfma_f32_16x16x32_bf16 v[62:65], v[150:153], v[182:185], v[62:65]
	v_mfma_f32_16x16x32_bf16 v[54:57], v[158:161], v[182:185], v[54:57]
	v_mfma_f32_16x16x32_bf16 v[46:49], v[150:153], v[196:199], v[46:49]
	v_mfma_f32_16x16x32_bf16 v[38:41], v[158:161], v[196:199], v[38:41]
	v_mfma_f32_16x16x32_bf16 v[30:33], v[150:153], v[204:207], v[30:33]
	v_mfma_f32_16x16x32_bf16 v[22:25], v[158:161], v[204:207], v[22:25]
	v_mfma_f32_16x16x32_bf16 v[14:17], v[150:153], v[212:215], v[14:17]
	v_mfma_f32_16x16x32_bf16 v[6:9], v[158:161], v[212:215], v[6:9]
	v_mfma_f32_16x16x32_bf16 v[62:65], v[154:157], v[192:195], v[62:65]
	v_mfma_f32_16x16x32_bf16 v[54:57], v[162:165], v[192:195], v[54:57]
	v_mfma_f32_16x16x32_bf16 v[46:49], v[154:157], v[200:203], v[46:49]
	v_mfma_f32_16x16x32_bf16 v[38:41], v[162:165], v[200:203], v[38:41]
	v_mfma_f32_16x16x32_bf16 v[30:33], v[154:157], v[208:211], v[30:33]
	v_mfma_f32_16x16x32_bf16 v[22:25], v[162:165], v[208:211], v[22:25]
	v_mfma_f32_16x16x32_bf16 v[14:17], v[154:157], v[216:219], v[14:17]
	v_mfma_f32_16x16x32_bf16 v[6:9], v[162:165], v[216:219], v[6:9]
	v_mfma_f32_16x16x32_bf16 v[58:61], v[166:169], v[182:185], v[58:61]
	v_mfma_f32_16x16x32_bf16 v[50:53], v[174:177], v[182:185], v[50:53]
	v_mfma_f32_16x16x32_bf16 v[42:45], v[166:169], v[196:199], v[42:45]
	v_mfma_f32_16x16x32_bf16 v[34:37], v[174:177], v[196:199], v[34:37]
	v_mfma_f32_16x16x32_bf16 v[26:29], v[166:169], v[204:207], v[26:29]
	v_mfma_f32_16x16x32_bf16 v[18:21], v[174:177], v[204:207], v[18:21]
	v_mfma_f32_16x16x32_bf16 v[10:13], v[166:169], v[212:215], v[10:13]
	v_mfma_f32_16x16x32_bf16 v[2:5], v[174:177], v[212:215], v[2:5]
	v_mfma_f32_16x16x32_bf16 v[58:61], v[170:173], v[192:195], v[58:61]
	v_mfma_f32_16x16x32_bf16 v[50:53], v[178:181], v[192:195], v[50:53]
	v_mfma_f32_16x16x32_bf16 v[42:45], v[170:173], v[200:203], v[42:45]
	v_mfma_f32_16x16x32_bf16 v[34:37], v[178:181], v[200:203], v[34:37]
	v_mfma_f32_16x16x32_bf16 v[26:29], v[170:173], v[208:211], v[26:29]
	v_mfma_f32_16x16x32_bf16 v[18:21], v[178:181], v[208:211], v[18:21]
	v_mfma_f32_16x16x32_bf16 v[10:13], v[170:173], v[216:219], v[10:13]
	v_mfma_f32_16x16x32_bf16 v[2:5], v[178:181], v[216:219], v[2:5]
	s_setprio 0
	s_barrier
	s_add_i32 s73, 0, 0x18000
	v_add_u32_e32 v149, s73, v146
	s_add_i32 s76, 0, 0x1c000
	ds_read_b128 v[150:153], v149
	ds_read_b128 v[154:157], v149 offset:1024
	ds_read_b128 v[158:161], v149 offset:2048
	ds_read_b128 v[162:165], v149 offset:3072
	v_add_u32_e32 v149, s76, v146
	ds_read_b128 v[166:169], v149
	ds_read_b128 v[170:173], v149 offset:1024
	ds_read_b128 v[174:177], v149 offset:2048
	ds_read_b128 v[178:181], v149 offset:3072
	s_add_u32 s74, s96, 0x40000
	s_addc_u32 s75, s97, 0
	s_mov_b32 m0, s42
	v_lshl_add_u64 v[238:239], s[74:75], 0, v[130:131]
	ds_read_b128 v[182:185], v148 offset:32768
	ds_read_b128 v[192:195], v148 offset:33792
	ds_read_b128 v[196:199], v148 offset:34816
	ds_read_b128 v[200:203], v148 offset:35840
	ds_read_b128 v[204:207], v148 offset:36864
	ds_read_b128 v[208:211], v148 offset:37888
	ds_read_b128 v[212:215], v148 offset:38912
	ds_read_b128 v[216:219], v148 offset:39936
	global_load_lds_dwordx4 v[238:239], off
	v_lshl_add_u64 v[238:239], s[74:75], 0, v[134:135]
	s_mov_b32 m0, s43
	s_nop 0
	global_load_lds_dwordx4 v[238:239], off
	s_waitcnt vmcnt(8)
	s_waitcnt lgkmcnt(0)
	s_barrier
	s_setprio 1
	s_waitcnt lgkmcnt(0)
	v_mfma_f32_16x16x32_bf16 v[126:129], v[150:153], v[182:185], v[126:129]
	v_mfma_f32_16x16x32_bf16 v[118:121], v[158:161], v[182:185], v[118:121]
	v_mfma_f32_16x16x32_bf16 v[110:113], v[150:153], v[196:199], v[110:113]
	v_mfma_f32_16x16x32_bf16 v[102:105], v[158:161], v[196:199], v[102:105]
	v_mfma_f32_16x16x32_bf16 v[94:97], v[150:153], v[204:207], v[94:97]
	v_mfma_f32_16x16x32_bf16 v[86:89], v[158:161], v[204:207], v[86:89]
	v_mfma_f32_16x16x32_bf16 v[78:81], v[150:153], v[212:215], v[78:81]
	v_mfma_f32_16x16x32_bf16 v[70:73], v[158:161], v[212:215], v[70:73]
	v_mfma_f32_16x16x32_bf16 v[126:129], v[154:157], v[192:195], v[126:129]
	v_mfma_f32_16x16x32_bf16 v[118:121], v[162:165], v[192:195], v[118:121]
	v_mfma_f32_16x16x32_bf16 v[110:113], v[154:157], v[200:203], v[110:113]
	v_mfma_f32_16x16x32_bf16 v[102:105], v[162:165], v[200:203], v[102:105]
	v_mfma_f32_16x16x32_bf16 v[94:97], v[154:157], v[208:211], v[94:97]
	v_mfma_f32_16x16x32_bf16 v[86:89], v[162:165], v[208:211], v[86:89]
	v_mfma_f32_16x16x32_bf16 v[78:81], v[154:157], v[216:219], v[78:81]
	v_mfma_f32_16x16x32_bf16 v[70:73], v[162:165], v[216:219], v[70:73]
	v_mfma_f32_16x16x32_bf16 v[122:125], v[166:169], v[182:185], v[122:125]
	v_mfma_f32_16x16x32_bf16 v[114:117], v[174:177], v[182:185], v[114:117]
	v_mfma_f32_16x16x32_bf16 v[106:109], v[166:169], v[196:199], v[106:109]
	v_mfma_f32_16x16x32_bf16 v[98:101], v[174:177], v[196:199], v[98:101]
	v_mfma_f32_16x16x32_bf16 v[90:93], v[166:169], v[204:207], v[90:93]
	v_mfma_f32_16x16x32_bf16 v[82:85], v[174:177], v[204:207], v[82:85]
	v_mfma_f32_16x16x32_bf16 v[74:77], v[166:169], v[212:215], v[74:77]
	v_mfma_f32_16x16x32_bf16 v[66:69], v[174:177], v[212:215], v[66:69]
	v_mfma_f32_16x16x32_bf16 v[122:125], v[170:173], v[192:195], v[122:125]
	v_mfma_f32_16x16x32_bf16 v[114:117], v[178:181], v[192:195], v[114:117]
	v_mfma_f32_16x16x32_bf16 v[106:109], v[170:173], v[200:203], v[106:109]
	v_mfma_f32_16x16x32_bf16 v[98:101], v[178:181], v[200:203], v[98:101]
	v_mfma_f32_16x16x32_bf16 v[90:93], v[170:173], v[208:211], v[90:93]
	v_mfma_f32_16x16x32_bf16 v[82:85], v[178:181], v[208:211], v[82:85]
	v_mfma_f32_16x16x32_bf16 v[74:77], v[170:173], v[216:219], v[74:77]
	v_mfma_f32_16x16x32_bf16 v[66:69], v[178:181], v[216:219], v[66:69]
	s_setprio 0
	s_barrier
	s_add_i32 s73, s73, s40
	v_lshl_add_u64 v[144:145], v[144:145], 0, s[94:95]
	s_mov_b32 m0, s73
	ds_read_b128 v[182:185], v148 offset:49152
	ds_read_b128 v[192:195], v148 offset:50176
	ds_read_b128 v[196:199], v148 offset:51200
	ds_read_b128 v[200:203], v148 offset:52224
	ds_read_b128 v[204:207], v148 offset:53248
	ds_read_b128 v[208:211], v148 offset:54272
	ds_read_b128 v[212:215], v148 offset:55296
	ds_read_b128 v[216:219], v148 offset:56320
	global_load_lds_dwordx4 v[144:145], off
	s_add_i32 m0, s73, 0x2000
	s_add_u32 s26, s26, 0x40080
	v_lshl_add_u64 v[144:145], v[186:187], 0, s[94:95]
	s_addc_u32 s27, s27, 0
	s_add_i32 s73, s76, s40
	global_load_lds_dwordx4 v[144:145], off
	v_lshl_add_u64 v[144:145], s[26:27], 0, v[132:133]
	s_mov_b32 m0, s73
	s_nop 0
	global_load_lds_dwordx4 v[144:145], off
	v_lshl_add_u64 v[144:145], s[26:27], 0, v[136:137]
	s_add_i32 m0, s73, 0x2000
	s_nop 0
	global_load_lds_dwordx4 v[144:145], off
	v_lshl_add_u64 v[144:145], v[220:221], 0, s[94:95]
	s_mov_b32 m0, s45
	s_nop 0
	global_load_lds_dwordx4 v[144:145], off
	v_lshl_add_u64 v[144:145], v[236:237], 0, s[94:95]
	s_mov_b32 m0, s50
	s_nop 0
	global_load_lds_dwordx4 v[144:145], off
	s_waitcnt vmcnt(8)
	s_waitcnt lgkmcnt(0)
	s_barrier
	s_setprio 1
	s_waitcnt lgkmcnt(0)
	v_mfma_f32_16x16x32_bf16 v[62:65], v[150:153], v[182:185], v[62:65]
	v_mfma_f32_16x16x32_bf16 v[54:57], v[158:161], v[182:185], v[54:57]
	v_mfma_f32_16x16x32_bf16 v[46:49], v[150:153], v[196:199], v[46:49]
	v_mfma_f32_16x16x32_bf16 v[38:41], v[158:161], v[196:199], v[38:41]
	v_mfma_f32_16x16x32_bf16 v[30:33], v[150:153], v[204:207], v[30:33]
	v_mfma_f32_16x16x32_bf16 v[22:25], v[158:161], v[204:207], v[22:25]
	v_mfma_f32_16x16x32_bf16 v[14:17], v[150:153], v[212:215], v[14:17]
	v_mfma_f32_16x16x32_bf16 v[6:9], v[158:161], v[212:215], v[6:9]
	v_mfma_f32_16x16x32_bf16 v[62:65], v[154:157], v[192:195], v[62:65]
	v_mfma_f32_16x16x32_bf16 v[54:57], v[162:165], v[192:195], v[54:57]
	v_mfma_f32_16x16x32_bf16 v[46:49], v[154:157], v[200:203], v[46:49]
	v_mfma_f32_16x16x32_bf16 v[38:41], v[162:165], v[200:203], v[38:41]
	v_mfma_f32_16x16x32_bf16 v[30:33], v[154:157], v[208:211], v[30:33]
	v_mfma_f32_16x16x32_bf16 v[22:25], v[162:165], v[208:211], v[22:25]
	v_mfma_f32_16x16x32_bf16 v[14:17], v[154:157], v[216:219], v[14:17]
	v_mfma_f32_16x16x32_bf16 v[6:9], v[162:165], v[216:219], v[6:9]
	v_mfma_f32_16x16x32_bf16 v[58:61], v[166:169], v[182:185], v[58:61]
	v_mfma_f32_16x16x32_bf16 v[50:53], v[174:177], v[182:185], v[50:53]
	v_mfma_f32_16x16x32_bf16 v[42:45], v[166:169], v[196:199], v[42:45]
	v_mfma_f32_16x16x32_bf16 v[34:37], v[174:177], v[196:199], v[34:37]
	v_mfma_f32_16x16x32_bf16 v[26:29], v[166:169], v[204:207], v[26:29]
	v_mfma_f32_16x16x32_bf16 v[18:21], v[174:177], v[204:207], v[18:21]
	v_mfma_f32_16x16x32_bf16 v[10:13], v[166:169], v[212:215], v[10:13]
	v_mfma_f32_16x16x32_bf16 v[2:5], v[174:177], v[212:215], v[2:5]
	v_mfma_f32_16x16x32_bf16 v[58:61], v[170:173], v[192:195], v[58:61]
	v_mfma_f32_16x16x32_bf16 v[50:53], v[178:181], v[192:195], v[50:53]
	v_mfma_f32_16x16x32_bf16 v[42:45], v[170:173], v[200:203], v[42:45]
	v_mfma_f32_16x16x32_bf16 v[34:37], v[178:181], v[200:203], v[34:37]
	v_mfma_f32_16x16x32_bf16 v[26:29], v[170:173], v[208:211], v[26:29]
	v_mfma_f32_16x16x32_bf16 v[18:21], v[178:181], v[208:211], v[18:21]
	v_mfma_f32_16x16x32_bf16 v[10:13], v[170:173], v[216:219], v[10:13]
	v_mfma_f32_16x16x32_bf16 v[2:5], v[178:181], v[216:219], v[2:5]
	s_setprio 0
	s_barrier
	s_add_i32 s72, s72, 2
	s_add_u32 s34, s34, 0x100
	s_addc_u32 s35, s35, 0
	s_add_u32 s63, s63, 0x100
	s_addc_u32 s65, s65, 0
	s_cmp_gt_u32 s72, 13
	s_cbranch_scc0 .LBB0_169
	s_and_b64 vcc, exec, s[8:9]
	s_cbranch_vccz .LBB0_172
	s_barrier

.LBB0_243:
	s_add_u32 s4, s24, 0x100
	s_addc_u32 s5, s25, 0
	s_add_i32 s87, 0, 0x10000
	s_cmp_eq_u32 s79, 40
	s_cselect_b32 s97, s35, s5
	s_cselect_b32 s96, s34, s4
	s_cselect_b32 s27, s23, s78
	s_cselect_b32 s26, s22, s77
	s_add_i32 s92, 0, 0x14000
	v_add_u32_e32 v170, s87, v235
	v_add_u32_e32 v186, s92, v235
	ds_read_b128 v[130:133], v170
	ds_read_b128 v[162:165], v170 offset:1024
	ds_read_b128 v[166:169], v170 offset:2048
	ds_read_b128 v[170:173], v170 offset:3072
	ds_read_b128 v[174:177], v186
	ds_read_b128 v[178:181], v186 offset:1024
	ds_read_b128 v[182:185], v186 offset:2048
	ds_read_b128 v[192:195], v186 offset:3072
	v_lshl_add_u64 v[186:187], s[24:25], 0, v[158:159]
	s_add_i32 m0, s37, 0xc000
	ds_read_b128 v[196:199], v237
	ds_read_b128 v[200:203], v237 offset:1024
	ds_read_b128 v[204:207], v237 offset:2048
	ds_read_b128 v[208:211], v237 offset:3072
	ds_read_b128 v[212:215], v237 offset:4096
	ds_read_b128 v[216:219], v237 offset:5120
	ds_read_b128 v[238:241], v237 offset:6144
	ds_read_b128 v[242:245], v237 offset:7168
	global_load_lds_dwordx4 v[186:187], off
	v_lshl_add_u64 v[186:187], s[24:25], 0, v[160:161]
	s_add_i32 m0, s37, 0xe000
	s_nop 0
	global_load_lds_dwordx4 v[186:187], off
	s_waitcnt vmcnt(8)
	s_waitcnt lgkmcnt(0)
	s_barrier
	s_setprio 1
	s_waitcnt lgkmcnt(0)
	v_mfma_f32_16x16x32_bf16 v[126:129], v[130:133], v[196:199], v[126:129]
	v_mfma_f32_16x16x32_bf16 v[94:97], v[166:169], v[196:199], v[94:97]
	v_mfma_f32_16x16x32_bf16 v[122:125], v[130:133], v[204:207], v[122:125]
	v_mfma_f32_16x16x32_bf16 v[90:93], v[166:169], v[204:207], v[90:93]
	v_mfma_f32_16x16x32_bf16 v[118:121], v[130:133], v[212:215], v[118:121]
	v_mfma_f32_16x16x32_bf16 v[86:89], v[166:169], v[212:215], v[86:89]
	v_mfma_f32_16x16x32_bf16 v[114:117], v[130:133], v[238:241], v[114:117]
	v_mfma_f32_16x16x32_bf16 v[82:85], v[166:169], v[238:241], v[82:85]
	v_mfma_f32_16x16x32_bf16 v[126:129], v[162:165], v[200:203], v[126:129]
	v_mfma_f32_16x16x32_bf16 v[94:97], v[170:173], v[200:203], v[94:97]
	v_mfma_f32_16x16x32_bf16 v[122:125], v[162:165], v[208:211], v[122:125]
	v_mfma_f32_16x16x32_bf16 v[90:93], v[170:173], v[208:211], v[90:93]
	v_mfma_f32_16x16x32_bf16 v[118:121], v[162:165], v[216:219], v[118:121]
	v_mfma_f32_16x16x32_bf16 v[86:89], v[170:173], v[216:219], v[86:89]
	v_mfma_f32_16x16x32_bf16 v[114:117], v[162:165], v[242:245], v[114:117]
	v_mfma_f32_16x16x32_bf16 v[82:85], v[170:173], v[242:245], v[82:85]
	v_mfma_f32_16x16x32_bf16 v[62:65], v[174:177], v[196:199], v[62:65]
	v_mfma_f32_16x16x32_bf16 v[30:33], v[182:185], v[196:199], v[30:33]
	v_mfma_f32_16x16x32_bf16 v[58:61], v[174:177], v[204:207], v[58:61]
	v_mfma_f32_16x16x32_bf16 v[26:29], v[182:185], v[204:207], v[26:29]
	v_mfma_f32_16x16x32_bf16 v[54:57], v[174:177], v[212:215], v[54:57]
	v_mfma_f32_16x16x32_bf16 v[22:25], v[182:185], v[212:215], v[22:25]
	v_mfma_f32_16x16x32_bf16 v[50:53], v[174:177], v[238:241], v[50:53]
	v_mfma_f32_16x16x32_bf16 v[18:21], v[182:185], v[238:241], v[18:21]
	v_mfma_f32_16x16x32_bf16 v[62:65], v[178:181], v[200:203], v[62:65]
	v_mfma_f32_16x16x32_bf16 v[30:33], v[192:195], v[200:203], v[30:33]
	v_mfma_f32_16x16x32_bf16 v[58:61], v[178:181], v[208:211], v[58:61]
	v_mfma_f32_16x16x32_bf16 v[26:29], v[192:195], v[208:211], v[26:29]
	v_mfma_f32_16x16x32_bf16 v[54:57], v[178:181], v[216:219], v[54:57]
	v_mfma_f32_16x16x32_bf16 v[22:25], v[192:195], v[216:219], v[22:25]
	v_mfma_f32_16x16x32_bf16 v[50:53], v[178:181], v[242:245], v[50:53]
	v_mfma_f32_16x16x32_bf16 v[18:21], v[192:195], v[242:245], v[18:21]
	s_setprio 0
	s_barrier
	s_add_i32 s24, s87, s29
	v_lshl_add_u64 v[186:187], s[26:27], 0, v[136:137]
	s_mov_b32 m0, s24
	ds_read_b128 v[196:199], v237 offset:16384
	ds_read_b128 v[200:203], v237 offset:17408
	ds_read_b128 v[204:207], v237 offset:18432
	ds_read_b128 v[208:211], v237 offset:19456
	ds_read_b128 v[212:215], v237 offset:20480
	ds_read_b128 v[216:219], v237 offset:21504
	ds_read_b128 v[238:241], v237 offset:22528
	ds_read_b128 v[242:245], v237 offset:23552
	global_load_lds_dwordx4 v[186:187], off
	s_add_i32 m0, s24, 0x2000
	s_add_u32 s24, s26, 0xb0000
	v_lshl_add_u64 v[220:221], s[26:27], 0, v[140:141]
	s_addc_u32 s25, s27, 0
	s_add_i32 s87, s92, s29
	global_load_lds_dwordx4 v[220:221], off
	v_lshl_add_u64 v[246:247], s[24:25], 0, v[136:137]
	s_mov_b32 m0, s87
	v_lshl_add_u64 v[248:249], s[96:97], 0, v[138:139]
	global_load_lds_dwordx4 v[246:247], off
	v_lshl_add_u64 v[246:247], s[24:25], 0, v[140:141]
	s_add_i32 m0, s87, 0x2000
	s_nop 0
	global_load_lds_dwordx4 v[246:247], off
	v_lshl_add_u64 v[246:247], s[96:97], 0, v[134:135]
	s_mov_b32 m0, s37
	s_nop 0
	global_load_lds_dwordx4 v[246:247], off
	s_mov_b32 m0, s38
	s_nop 0
	global_load_lds_dwordx4 v[248:249], off
	s_waitcnt vmcnt(8)
	s_waitcnt lgkmcnt(0)
	s_barrier
	s_setprio 1
	s_waitcnt lgkmcnt(0)
	v_mfma_f32_16x16x32_bf16 v[110:113], v[130:133], v[196:199], v[110:113]
	v_mfma_f32_16x16x32_bf16 v[78:81], v[166:169], v[196:199], v[78:81]
	v_mfma_f32_16x16x32_bf16 v[106:109], v[130:133], v[204:207], v[106:109]
	v_mfma_f32_16x16x32_bf16 v[74:77], v[166:169], v[204:207], v[74:77]
	v_mfma_f32_16x16x32_bf16 v[102:105], v[130:133], v[212:215], v[102:105]
	v_mfma_f32_16x16x32_bf16 v[70:73], v[166:169], v[212:215], v[70:73]
	v_mfma_f32_16x16x32_bf16 v[98:101], v[130:133], v[238:241], v[98:101]
	v_mfma_f32_16x16x32_bf16 v[66:69], v[166:169], v[238:241], v[66:69]
	v_mfma_f32_16x16x32_bf16 v[110:113], v[162:165], v[200:203], v[110:113]
	v_mfma_f32_16x16x32_bf16 v[78:81], v[170:173], v[200:203], v[78:81]
	v_mfma_f32_16x16x32_bf16 v[106:109], v[162:165], v[208:211], v[106:109]
	v_mfma_f32_16x16x32_bf16 v[74:77], v[170:173], v[208:211], v[74:77]
	v_mfma_f32_16x16x32_bf16 v[102:105], v[162:165], v[216:219], v[102:105]
	v_mfma_f32_16x16x32_bf16 v[70:73], v[170:173], v[216:219], v[70:73]
	v_mfma_f32_16x16x32_bf16 v[98:101], v[162:165], v[242:245], v[98:101]
	v_mfma_f32_16x16x32_bf16 v[66:69], v[170:173], v[242:245], v[66:69]
	v_mfma_f32_16x16x32_bf16 v[46:49], v[174:177], v[196:199], v[46:49]
	v_mfma_f32_16x16x32_bf16 v[14:17], v[182:185], v[196:199], v[14:17]
	v_mfma_f32_16x16x32_bf16 v[42:45], v[174:177], v[204:207], v[42:45]
	v_mfma_f32_16x16x32_bf16 v[10:13], v[182:185], v[204:207], v[10:13]
	v_mfma_f32_16x16x32_bf16 v[38:41], v[174:177], v[212:215], v[38:41]
	v_mfma_f32_16x16x32_bf16 v[6:9], v[182:185], v[212:215], v[6:9]
	v_mfma_f32_16x16x32_bf16 v[34:37], v[174:177], v[238:241], v[34:37]
	v_mfma_f32_16x16x32_bf16 v[2:5], v[182:185], v[238:241], v[2:5]
	v_mfma_f32_16x16x32_bf16 v[46:49], v[178:181], v[200:203], v[46:49]
	v_mfma_f32_16x16x32_bf16 v[14:17], v[192:195], v[200:203], v[14:17]
	v_mfma_f32_16x16x32_bf16 v[42:45], v[178:181], v[208:211], v[42:45]
	v_mfma_f32_16x16x32_bf16 v[10:13], v[192:195], v[208:211], v[10:13]
	v_mfma_f32_16x16x32_bf16 v[38:41], v[178:181], v[216:219], v[38:41]
	v_mfma_f32_16x16x32_bf16 v[6:9], v[192:195], v[216:219], v[6:9]
	v_mfma_f32_16x16x32_bf16 v[34:37], v[178:181], v[242:245], v[34:37]
	v_mfma_f32_16x16x32_bf16 v[2:5], v[192:195], v[242:245], v[2:5]
	s_setprio 0
	s_barrier
	s_add_i32 s87, 0, 0x18000
	s_add_i32 s92, 0, 0x1c000
	v_add_u32_e32 v170, s87, v235
	v_add_u32_e32 v192, s92, v235
	ds_read_b128 v[130:133], v170
	ds_read_b128 v[162:165], v170 offset:1024
	ds_read_b128 v[166:169], v170 offset:2048
	ds_read_b128 v[170:173], v170 offset:3072
	ds_read_b128 v[174:177], v192
	ds_read_b128 v[178:181], v192 offset:1024
	ds_read_b128 v[182:185], v192 offset:2048
	ds_read_b128 v[192:195], v192 offset:3072
	s_add_u32 s24, s96, 0xb0000
	s_addc_u32 s25, s97, 0
	s_mov_b32 m0, s39
	v_lshl_add_u64 v[250:251], s[24:25], 0, v[134:135]
	ds_read_b128 v[196:199], v237 offset:32768
	ds_read_b128 v[200:203], v237 offset:33792
	ds_read_b128 v[204:207], v237 offset:34816
	ds_read_b128 v[208:211], v237 offset:35840
	ds_read_b128 v[212:215], v237 offset:36864
	ds_read_b128 v[216:219], v237 offset:37888
	ds_read_b128 v[238:241], v237 offset:38912
	ds_read_b128 v[242:245], v237 offset:39936
	global_load_lds_dwordx4 v[250:251], off
	v_lshl_add_u64 v[250:251], s[24:25], 0, v[138:139]
	s_mov_b32 m0, s40
	s_nop 0
	global_load_lds_dwordx4 v[250:251], off
	s_waitcnt vmcnt(8)
	s_waitcnt lgkmcnt(0)
	s_barrier
	s_setprio 1
	s_waitcnt lgkmcnt(0)
	v_mfma_f32_16x16x32_bf16 v[126:129], v[130:133], v[196:199], v[126:129]
	v_mfma_f32_16x16x32_bf16 v[94:97], v[166:169], v[196:199], v[94:97]
	v_mfma_f32_16x16x32_bf16 v[122:125], v[130:133], v[204:207], v[122:125]
	v_mfma_f32_16x16x32_bf16 v[90:93], v[166:169], v[204:207], v[90:93]
	v_mfma_f32_16x16x32_bf16 v[118:121], v[130:133], v[212:215], v[118:121]
	v_mfma_f32_16x16x32_bf16 v[86:89], v[166:169], v[212:215], v[86:89]
	v_mfma_f32_16x16x32_bf16 v[114:117], v[130:133], v[238:241], v[114:117]
	v_mfma_f32_16x16x32_bf16 v[82:85], v[166:169], v[238:241], v[82:85]
	v_mfma_f32_16x16x32_bf16 v[126:129], v[162:165], v[200:203], v[126:129]
	v_mfma_f32_16x16x32_bf16 v[94:97], v[170:173], v[200:203], v[94:97]
	v_mfma_f32_16x16x32_bf16 v[122:125], v[162:165], v[208:211], v[122:125]
	v_mfma_f32_16x16x32_bf16 v[90:93], v[170:173], v[208:211], v[90:93]
	v_mfma_f32_16x16x32_bf16 v[118:121], v[162:165], v[216:219], v[118:121]
	v_mfma_f32_16x16x32_bf16 v[86:89], v[170:173], v[216:219], v[86:89]
	v_mfma_f32_16x16x32_bf16 v[114:117], v[162:165], v[242:245], v[114:117]
	v_mfma_f32_16x16x32_bf16 v[82:85], v[170:173], v[242:245], v[82:85]
	v_mfma_f32_16x16x32_bf16 v[62:65], v[174:177], v[196:199], v[62:65]
	v_mfma_f32_16x16x32_bf16 v[30:33], v[182:185], v[196:199], v[30:33]
	v_mfma_f32_16x16x32_bf16 v[58:61], v[174:177], v[204:207], v[58:61]
	v_mfma_f32_16x16x32_bf16 v[26:29], v[182:185], v[204:207], v[26:29]
	v_mfma_f32_16x16x32_bf16 v[54:57], v[174:177], v[212:215], v[54:57]
	v_mfma_f32_16x16x32_bf16 v[22:25], v[182:185], v[212:215], v[22:25]
	v_mfma_f32_16x16x32_bf16 v[50:53], v[174:177], v[238:241], v[50:53]
	v_mfma_f32_16x16x32_bf16 v[18:21], v[182:185], v[238:241], v[18:21]
	v_mfma_f32_16x16x32_bf16 v[62:65], v[178:181], v[200:203], v[62:65]
	v_mfma_f32_16x16x32_bf16 v[30:33], v[192:195], v[200:203], v[30:33]
	v_mfma_f32_16x16x32_bf16 v[58:61], v[178:181], v[208:211], v[58:61]
	v_mfma_f32_16x16x32_bf16 v[26:29], v[192:195], v[208:211], v[26:29]
	v_mfma_f32_16x16x32_bf16 v[54:57], v[178:181], v[216:219], v[54:57]
	v_mfma_f32_16x16x32_bf16 v[22:25], v[192:195], v[216:219], v[22:25]
	v_mfma_f32_16x16x32_bf16 v[50:53], v[178:181], v[242:245], v[50:53]
	v_mfma_f32_16x16x32_bf16 v[18:21], v[192:195], v[242:245], v[18:21]
	s_setprio 0
	s_barrier
	s_add_i32 s24, s87, s29
	v_lshl_add_u64 v[186:187], v[186:187], 0, s[94:95]
	s_mov_b32 m0, s24
	ds_read_b128 v[196:199], v237 offset:49152
	ds_read_b128 v[200:203], v237 offset:50176
	ds_read_b128 v[204:207], v237 offset:51200
	ds_read_b128 v[208:211], v237 offset:52224
	ds_read_b128 v[212:215], v237 offset:53248
	ds_read_b128 v[216:219], v237 offset:54272
	ds_read_b128 v[238:241], v237 offset:55296
	ds_read_b128 v[242:245], v237 offset:56320
	global_load_lds_dwordx4 v[186:187], off
	s_add_i32 m0, s24, 0x2000
	s_add_u32 s24, s26, 0xb0080
	v_lshl_add_u64 v[186:187], v[220:221], 0, s[94:95]
	s_addc_u32 s25, s27, 0
	s_add_i32 s26, s92, s29
	global_load_lds_dwordx4 v[186:187], off
	v_lshl_add_u64 v[186:187], s[24:25], 0, v[136:137]
	s_mov_b32 m0, s26
	s_nop 0
	global_load_lds_dwordx4 v[186:187], off
	v_lshl_add_u64 v[186:187], s[24:25], 0, v[140:141]
	s_add_i32 m0, s26, 0x2000
	s_nop 0
	global_load_lds_dwordx4 v[186:187], off
	v_lshl_add_u64 v[186:187], v[246:247], 0, s[94:95]
	s_mov_b32 m0, s63
	s_nop 0
	global_load_lds_dwordx4 v[186:187], off
	v_lshl_add_u64 v[186:187], v[248:249], 0, s[94:95]
	s_mov_b32 m0, s65
	s_nop 0
	global_load_lds_dwordx4 v[186:187], off
	s_waitcnt vmcnt(8)
	s_waitcnt lgkmcnt(0)
	s_barrier
	s_setprio 1
	s_waitcnt lgkmcnt(0)
	v_mfma_f32_16x16x32_bf16 v[110:113], v[130:133], v[196:199], v[110:113]
	v_mfma_f32_16x16x32_bf16 v[78:81], v[166:169], v[196:199], v[78:81]
	v_mfma_f32_16x16x32_bf16 v[106:109], v[130:133], v[204:207], v[106:109]
	v_mfma_f32_16x16x32_bf16 v[74:77], v[166:169], v[204:207], v[74:77]
	v_mfma_f32_16x16x32_bf16 v[102:105], v[130:133], v[212:215], v[102:105]
	v_mfma_f32_16x16x32_bf16 v[70:73], v[166:169], v[212:215], v[70:73]
	v_mfma_f32_16x16x32_bf16 v[98:101], v[130:133], v[238:241], v[98:101]
	v_mfma_f32_16x16x32_bf16 v[66:69], v[166:169], v[238:241], v[66:69]
	v_mfma_f32_16x16x32_bf16 v[110:113], v[162:165], v[200:203], v[110:113]
	v_mfma_f32_16x16x32_bf16 v[78:81], v[170:173], v[200:203], v[78:81]
	v_mfma_f32_16x16x32_bf16 v[106:109], v[162:165], v[208:211], v[106:109]
	v_mfma_f32_16x16x32_bf16 v[74:77], v[170:173], v[208:211], v[74:77]
	v_mfma_f32_16x16x32_bf16 v[102:105], v[162:165], v[216:219], v[102:105]
	v_mfma_f32_16x16x32_bf16 v[70:73], v[170:173], v[216:219], v[70:73]
	v_mfma_f32_16x16x32_bf16 v[98:101], v[162:165], v[242:245], v[98:101]
	v_mfma_f32_16x16x32_bf16 v[66:69], v[170:173], v[242:245], v[66:69]
	v_mfma_f32_16x16x32_bf16 v[46:49], v[174:177], v[196:199], v[46:49]
	v_mfma_f32_16x16x32_bf16 v[14:17], v[182:185], v[196:199], v[14:17]
	v_mfma_f32_16x16x32_bf16 v[42:45], v[174:177], v[204:207], v[42:45]
	v_mfma_f32_16x16x32_bf16 v[10:13], v[182:185], v[204:207], v[10:13]
	v_mfma_f32_16x16x32_bf16 v[38:41], v[174:177], v[212:215], v[38:41]
	v_mfma_f32_16x16x32_bf16 v[6:9], v[182:185], v[212:215], v[6:9]
	v_mfma_f32_16x16x32_bf16 v[34:37], v[174:177], v[238:241], v[34:37]
	v_mfma_f32_16x16x32_bf16 v[2:5], v[182:185], v[238:241], v[2:5]
	v_mfma_f32_16x16x32_bf16 v[46:49], v[178:181], v[200:203], v[46:49]
	v_mfma_f32_16x16x32_bf16 v[14:17], v[192:195], v[200:203], v[14:17]
	v_mfma_f32_16x16x32_bf16 v[42:45], v[178:181], v[208:211], v[42:45]
	v_mfma_f32_16x16x32_bf16 v[10:13], v[192:195], v[208:211], v[10:13]
	v_mfma_f32_16x16x32_bf16 v[38:41], v[178:181], v[216:219], v[38:41]
	v_mfma_f32_16x16x32_bf16 v[6:9], v[192:195], v[216:219], v[6:9]
	v_mfma_f32_16x16x32_bf16 v[34:37], v[178:181], v[242:245], v[34:37]
	v_mfma_f32_16x16x32_bf16 v[2:5], v[192:195], v[242:245], v[2:5]
	s_setprio 0
	s_barrier
	s_add_i32 s79, s79, 2
	s_add_u32 s77, s77, 0x100
	s_addc_u32 s78, s78, 0
	s_cmp_gt_u32 s79, 41
	s_mov_b64 s[24:25], s[4:5]
	s_cbranch_scc0 .LBB0_243
	s_and_b64 vcc, exec, s[30:31]
	s_cbranch_vccz .LBB0_246
	s_barrier

.LBB0_470:
	s_add_u32 s24, s22, 0xfffc0080
	s_addc_u32 s25, s23, -1
	s_add_i32 s42, 0, 0x10000
	s_cmp_eq_u32 s41, 12
	s_cselect_b32 s27, s11, s25
	s_cselect_b32 s26, s37, s24
	v_add_u32_e32 v142, s42, v144
	s_cselect_b32 s25, s9, s40
	s_cselect_b32 s24, s38, s39
	s_add_i32 s45, 0, 0x14000
	ds_read_b128 v[148:151], v142
	ds_read_b128 v[152:155], v142 offset:1024
	ds_read_b128 v[156:159], v142 offset:2048
	ds_read_b128 v[160:163], v142 offset:3072
	v_add_u32_e32 v142, s45, v144
	ds_read_b128 v[164:167], v142
	ds_read_b128 v[168:171], v142 offset:1024
	ds_read_b128 v[172:175], v142 offset:2048
	ds_read_b128 v[176:179], v142 offset:3072
	v_lshl_add_u64 v[142:143], s[22:23], 0, v[138:139]
	s_add_i32 m0, s18, 0xc000
	ds_read_b128 v[180:183], v146
	ds_read_b128 v[184:187], v146 offset:1024
	ds_read_b128 v[192:195], v146 offset:2048
	ds_read_b128 v[196:199], v146 offset:3072
	ds_read_b128 v[200:203], v146 offset:4096
	ds_read_b128 v[204:207], v146 offset:5120
	ds_read_b128 v[208:211], v146 offset:6144
	ds_read_b128 v[212:215], v146 offset:7168
	global_load_lds_dwordx4 v[142:143], off
	v_lshl_add_u64 v[142:143], s[22:23], 0, v[140:141]
	s_add_i32 m0, s18, 0xe000
	s_nop 0
	global_load_lds_dwordx4 v[142:143], off
	s_waitcnt vmcnt(8)
	s_waitcnt lgkmcnt(0)
	s_barrier
	s_setprio 1
	s_waitcnt lgkmcnt(0)
	v_mfma_f32_16x16x32_bf16 v[126:129], v[148:151], v[180:183], v[126:129]
	v_mfma_f32_16x16x32_bf16 v[122:125], v[156:159], v[180:183], v[122:125]
	v_mfma_f32_16x16x32_bf16 v[114:117], v[148:151], v[192:195], v[114:117]
	v_mfma_f32_16x16x32_bf16 v[106:109], v[156:159], v[192:195], v[106:109]
	v_mfma_f32_16x16x32_bf16 v[98:101], v[148:151], v[200:203], v[98:101]
	v_mfma_f32_16x16x32_bf16 v[90:93], v[156:159], v[200:203], v[90:93]
	v_mfma_f32_16x16x32_bf16 v[82:85], v[148:151], v[208:211], v[82:85]
	v_mfma_f32_16x16x32_bf16 v[74:77], v[156:159], v[208:211], v[74:77]
	v_mfma_f32_16x16x32_bf16 v[126:129], v[152:155], v[184:187], v[126:129]
	v_mfma_f32_16x16x32_bf16 v[122:125], v[160:163], v[184:187], v[122:125]
	v_mfma_f32_16x16x32_bf16 v[114:117], v[152:155], v[196:199], v[114:117]
	v_mfma_f32_16x16x32_bf16 v[106:109], v[160:163], v[196:199], v[106:109]
	v_mfma_f32_16x16x32_bf16 v[98:101], v[152:155], v[204:207], v[98:101]
	v_mfma_f32_16x16x32_bf16 v[90:93], v[160:163], v[204:207], v[90:93]
	v_mfma_f32_16x16x32_bf16 v[82:85], v[152:155], v[212:215], v[82:85]
	v_mfma_f32_16x16x32_bf16 v[74:77], v[160:163], v[212:215], v[74:77]
	v_mfma_f32_16x16x32_bf16 v[118:121], v[164:167], v[180:183], v[118:121]
	v_mfma_f32_16x16x32_bf16 v[110:113], v[172:175], v[180:183], v[110:113]
	v_mfma_f32_16x16x32_bf16 v[102:105], v[164:167], v[192:195], v[102:105]
	v_mfma_f32_16x16x32_bf16 v[94:97], v[172:175], v[192:195], v[94:97]
	v_mfma_f32_16x16x32_bf16 v[86:89], v[164:167], v[200:203], v[86:89]
	v_mfma_f32_16x16x32_bf16 v[78:81], v[172:175], v[200:203], v[78:81]
	v_mfma_f32_16x16x32_bf16 v[70:73], v[164:167], v[208:211], v[70:73]
	v_mfma_f32_16x16x32_bf16 v[66:69], v[172:175], v[208:211], v[66:69]
	v_mfma_f32_16x16x32_bf16 v[118:121], v[168:171], v[184:187], v[118:121]
	v_mfma_f32_16x16x32_bf16 v[110:113], v[176:179], v[184:187], v[110:113]
	v_mfma_f32_16x16x32_bf16 v[102:105], v[168:171], v[196:199], v[102:105]
	v_mfma_f32_16x16x32_bf16 v[94:97], v[176:179], v[196:199], v[94:97]
	v_mfma_f32_16x16x32_bf16 v[86:89], v[168:171], v[204:207], v[86:89]
	v_mfma_f32_16x16x32_bf16 v[78:81], v[176:179], v[204:207], v[78:81]
	v_mfma_f32_16x16x32_bf16 v[70:73], v[168:171], v[212:215], v[70:73]
	v_mfma_f32_16x16x32_bf16 v[66:69], v[176:179], v[212:215], v[66:69]
	s_setprio 0
	s_barrier
	s_add_i32 s42, s42, s2
	v_lshl_add_u64 v[142:143], s[24:25], 0, v[134:135]
	s_mov_b32 m0, s42
	ds_read_b128 v[180:183], v146 offset:16384
	ds_read_b128 v[184:187], v146 offset:17408
	ds_read_b128 v[192:195], v146 offset:18432
	ds_read_b128 v[196:199], v146 offset:19456
	ds_read_b128 v[200:203], v146 offset:20480
	ds_read_b128 v[204:207], v146 offset:21504
	ds_read_b128 v[208:211], v146 offset:22528
	ds_read_b128 v[212:215], v146 offset:23552
	global_load_lds_dwordx4 v[142:143], off
	s_add_i32 m0, s42, 0x2000
	s_add_u32 s42, s24, 0x40000
	v_lshl_add_u64 v[216:217], s[24:25], 0, v[130:131]
	s_addc_u32 s43, s25, 0
	s_add_i32 s45, s45, s2
	global_load_lds_dwordx4 v[216:217], off
	v_lshl_add_u64 v[218:219], s[42:43], 0, v[134:135]
	s_mov_b32 m0, s45
	v_lshl_add_u64 v[220:221], s[26:27], 0, v[132:133]
	global_load_lds_dwordx4 v[218:219], off
	v_lshl_add_u64 v[218:219], s[42:43], 0, v[130:131]
	s_add_i32 m0, s45, 0x2000
	s_nop 0
	global_load_lds_dwordx4 v[218:219], off
	v_lshl_add_u64 v[218:219], s[26:27], 0, v[136:137]
	s_mov_b32 m0, s18
	s_nop 0
	global_load_lds_dwordx4 v[218:219], off
	s_mov_b32 m0, s19
	s_nop 0
	global_load_lds_dwordx4 v[220:221], off
	s_waitcnt vmcnt(8)
	s_waitcnt lgkmcnt(0)
	s_barrier
	s_setprio 1
	s_waitcnt lgkmcnt(0)
	v_mfma_f32_16x16x32_bf16 v[62:65], v[148:151], v[180:183], v[62:65]
	v_mfma_f32_16x16x32_bf16 v[58:61], v[156:159], v[180:183], v[58:61]
	v_mfma_f32_16x16x32_bf16 v[50:53], v[148:151], v[192:195], v[50:53]
	v_mfma_f32_16x16x32_bf16 v[42:45], v[156:159], v[192:195], v[42:45]
	v_mfma_f32_16x16x32_bf16 v[34:37], v[148:151], v[200:203], v[34:37]
	v_mfma_f32_16x16x32_bf16 v[26:29], v[156:159], v[200:203], v[26:29]
	v_mfma_f32_16x16x32_bf16 v[18:21], v[148:151], v[208:211], v[18:21]
	v_mfma_f32_16x16x32_bf16 v[10:13], v[156:159], v[208:211], v[10:13]
	v_mfma_f32_16x16x32_bf16 v[62:65], v[152:155], v[184:187], v[62:65]
	v_mfma_f32_16x16x32_bf16 v[58:61], v[160:163], v[184:187], v[58:61]
	v_mfma_f32_16x16x32_bf16 v[50:53], v[152:155], v[196:199], v[50:53]
	v_mfma_f32_16x16x32_bf16 v[42:45], v[160:163], v[196:199], v[42:45]
	v_mfma_f32_16x16x32_bf16 v[34:37], v[152:155], v[204:207], v[34:37]
	v_mfma_f32_16x16x32_bf16 v[26:29], v[160:163], v[204:207], v[26:29]
	v_mfma_f32_16x16x32_bf16 v[18:21], v[152:155], v[212:215], v[18:21]
	v_mfma_f32_16x16x32_bf16 v[10:13], v[160:163], v[212:215], v[10:13]
	v_mfma_f32_16x16x32_bf16 v[54:57], v[164:167], v[180:183], v[54:57]
	v_mfma_f32_16x16x32_bf16 v[46:49], v[172:175], v[180:183], v[46:49]
	v_mfma_f32_16x16x32_bf16 v[38:41], v[164:167], v[192:195], v[38:41]
	v_mfma_f32_16x16x32_bf16 v[30:33], v[172:175], v[192:195], v[30:33]
	v_mfma_f32_16x16x32_bf16 v[22:25], v[164:167], v[200:203], v[22:25]
	v_mfma_f32_16x16x32_bf16 v[14:17], v[172:175], v[200:203], v[14:17]
	v_mfma_f32_16x16x32_bf16 v[6:9], v[164:167], v[208:211], v[6:9]
	v_mfma_f32_16x16x32_bf16 v[2:5], v[172:175], v[208:211], v[2:5]
	v_mfma_f32_16x16x32_bf16 v[54:57], v[168:171], v[184:187], v[54:57]
	v_mfma_f32_16x16x32_bf16 v[46:49], v[176:179], v[184:187], v[46:49]
	v_mfma_f32_16x16x32_bf16 v[38:41], v[168:171], v[196:199], v[38:41]
	v_mfma_f32_16x16x32_bf16 v[30:33], v[176:179], v[196:199], v[30:33]
	v_mfma_f32_16x16x32_bf16 v[22:25], v[168:171], v[204:207], v[22:25]
	v_mfma_f32_16x16x32_bf16 v[14:17], v[176:179], v[204:207], v[14:17]
	v_mfma_f32_16x16x32_bf16 v[6:9], v[168:171], v[212:215], v[6:9]
	v_mfma_f32_16x16x32_bf16 v[2:5], v[176:179], v[212:215], v[2:5]
	s_setprio 0
	s_barrier
	s_add_i32 s42, 0, 0x18000
	v_add_u32_e32 v147, s42, v144
	s_add_i32 s43, 0, 0x1c000
	ds_read_b128 v[148:151], v147
	ds_read_b128 v[152:155], v147 offset:1024
	ds_read_b128 v[156:159], v147 offset:2048
	ds_read_b128 v[160:163], v147 offset:3072
	v_add_u32_e32 v147, s43, v144
	ds_read_b128 v[164:167], v147
	ds_read_b128 v[168:171], v147 offset:1024
	ds_read_b128 v[172:175], v147 offset:2048
	ds_read_b128 v[176:179], v147 offset:3072
	s_add_u32 s26, s26, 0x40000
	s_addc_u32 s27, s27, 0
	s_mov_b32 m0, s28
	v_lshl_add_u64 v[236:237], s[26:27], 0, v[136:137]
	ds_read_b128 v[180:183], v146 offset:32768
	ds_read_b128 v[184:187], v146 offset:33792
	ds_read_b128 v[192:195], v146 offset:34816
	ds_read_b128 v[196:199], v146 offset:35840
	ds_read_b128 v[200:203], v146 offset:36864
	ds_read_b128 v[204:207], v146 offset:37888
	ds_read_b128 v[208:211], v146 offset:38912
	ds_read_b128 v[212:215], v146 offset:39936
	global_load_lds_dwordx4 v[236:237], off
	v_lshl_add_u64 v[236:237], s[26:27], 0, v[132:133]
	s_mov_b32 m0, s29
	s_nop 0
	global_load_lds_dwordx4 v[236:237], off
	s_waitcnt vmcnt(8)
	s_waitcnt lgkmcnt(0)
	s_barrier
	s_setprio 1
	s_waitcnt lgkmcnt(0)
	v_mfma_f32_16x16x32_bf16 v[126:129], v[148:151], v[180:183], v[126:129]
	v_mfma_f32_16x16x32_bf16 v[122:125], v[156:159], v[180:183], v[122:125]
	v_mfma_f32_16x16x32_bf16 v[114:117], v[148:151], v[192:195], v[114:117]
	v_mfma_f32_16x16x32_bf16 v[106:109], v[156:159], v[192:195], v[106:109]
	v_mfma_f32_16x16x32_bf16 v[98:101], v[148:151], v[200:203], v[98:101]
	v_mfma_f32_16x16x32_bf16 v[90:93], v[156:159], v[200:203], v[90:93]
	v_mfma_f32_16x16x32_bf16 v[82:85], v[148:151], v[208:211], v[82:85]
	v_mfma_f32_16x16x32_bf16 v[74:77], v[156:159], v[208:211], v[74:77]
	v_mfma_f32_16x16x32_bf16 v[126:129], v[152:155], v[184:187], v[126:129]
	v_mfma_f32_16x16x32_bf16 v[122:125], v[160:163], v[184:187], v[122:125]
	v_mfma_f32_16x16x32_bf16 v[114:117], v[152:155], v[196:199], v[114:117]
	v_mfma_f32_16x16x32_bf16 v[106:109], v[160:163], v[196:199], v[106:109]
	v_mfma_f32_16x16x32_bf16 v[98:101], v[152:155], v[204:207], v[98:101]
	v_mfma_f32_16x16x32_bf16 v[90:93], v[160:163], v[204:207], v[90:93]
	v_mfma_f32_16x16x32_bf16 v[82:85], v[152:155], v[212:215], v[82:85]
	v_mfma_f32_16x16x32_bf16 v[74:77], v[160:163], v[212:215], v[74:77]
	v_mfma_f32_16x16x32_bf16 v[118:121], v[164:167], v[180:183], v[118:121]
	v_mfma_f32_16x16x32_bf16 v[110:113], v[172:175], v[180:183], v[110:113]
	v_mfma_f32_16x16x32_bf16 v[102:105], v[164:167], v[192:195], v[102:105]
	v_mfma_f32_16x16x32_bf16 v[94:97], v[172:175], v[192:195], v[94:97]
	v_mfma_f32_16x16x32_bf16 v[86:89], v[164:167], v[200:203], v[86:89]
	v_mfma_f32_16x16x32_bf16 v[78:81], v[172:175], v[200:203], v[78:81]
	v_mfma_f32_16x16x32_bf16 v[70:73], v[164:167], v[208:211], v[70:73]
	v_mfma_f32_16x16x32_bf16 v[66:69], v[172:175], v[208:211], v[66:69]
	v_mfma_f32_16x16x32_bf16 v[118:121], v[168:171], v[184:187], v[118:121]
	v_mfma_f32_16x16x32_bf16 v[110:113], v[176:179], v[184:187], v[110:113]
	v_mfma_f32_16x16x32_bf16 v[102:105], v[168:171], v[196:199], v[102:105]
	v_mfma_f32_16x16x32_bf16 v[94:97], v[176:179], v[196:199], v[94:97]
	v_mfma_f32_16x16x32_bf16 v[86:89], v[168:171], v[204:207], v[86:89]
	v_mfma_f32_16x16x32_bf16 v[78:81], v[176:179], v[204:207], v[78:81]
	v_mfma_f32_16x16x32_bf16 v[70:73], v[168:171], v[212:215], v[70:73]
	v_mfma_f32_16x16x32_bf16 v[66:69], v[176:179], v[212:215], v[66:69]
	s_setprio 0
	s_barrier
	s_add_i32 s26, s42, s2
	v_lshl_add_u64 v[142:143], v[142:143], 0, s[94:95]
	s_mov_b32 m0, s26
	ds_read_b128 v[180:183], v146 offset:49152
	ds_read_b128 v[184:187], v146 offset:50176
	ds_read_b128 v[192:195], v146 offset:51200
	ds_read_b128 v[196:199], v146 offset:52224
	ds_read_b128 v[200:203], v146 offset:53248
	ds_read_b128 v[204:207], v146 offset:54272
	ds_read_b128 v[208:211], v146 offset:55296
	ds_read_b128 v[212:215], v146 offset:56320
	global_load_lds_dwordx4 v[142:143], off
	s_add_i32 m0, s26, 0x2000
	s_add_u32 s24, s24, 0x40080
	v_lshl_add_u64 v[142:143], v[216:217], 0, s[94:95]
	s_addc_u32 s25, s25, 0
	s_add_i32 s26, s43, s2
	global_load_lds_dwordx4 v[142:143], off
	v_lshl_add_u64 v[142:143], s[24:25], 0, v[134:135]
	s_mov_b32 m0, s26
	s_nop 0
	global_load_lds_dwordx4 v[142:143], off
	v_lshl_add_u64 v[142:143], s[24:25], 0, v[130:131]
	s_add_i32 m0, s26, 0x2000
	s_nop 0
	global_load_lds_dwordx4 v[142:143], off
	v_lshl_add_u64 v[142:143], v[218:219], 0, s[94:95]
	s_mov_b32 m0, s30
	s_nop 0
	global_load_lds_dwordx4 v[142:143], off
	v_lshl_add_u64 v[142:143], v[220:221], 0, s[94:95]
	s_mov_b32 m0, s31
	s_nop 0
	global_load_lds_dwordx4 v[142:143], off
	s_waitcnt vmcnt(8)
	s_waitcnt lgkmcnt(0)
	s_barrier
	s_setprio 1
	s_waitcnt lgkmcnt(0)
	v_mfma_f32_16x16x32_bf16 v[62:65], v[148:151], v[180:183], v[62:65]
	v_mfma_f32_16x16x32_bf16 v[58:61], v[156:159], v[180:183], v[58:61]
	v_mfma_f32_16x16x32_bf16 v[50:53], v[148:151], v[192:195], v[50:53]
	v_mfma_f32_16x16x32_bf16 v[42:45], v[156:159], v[192:195], v[42:45]
	v_mfma_f32_16x16x32_bf16 v[34:37], v[148:151], v[200:203], v[34:37]
	v_mfma_f32_16x16x32_bf16 v[26:29], v[156:159], v[200:203], v[26:29]
	v_mfma_f32_16x16x32_bf16 v[18:21], v[148:151], v[208:211], v[18:21]
	v_mfma_f32_16x16x32_bf16 v[10:13], v[156:159], v[208:211], v[10:13]
	v_mfma_f32_16x16x32_bf16 v[62:65], v[152:155], v[184:187], v[62:65]
	v_mfma_f32_16x16x32_bf16 v[58:61], v[160:163], v[184:187], v[58:61]
	v_mfma_f32_16x16x32_bf16 v[50:53], v[152:155], v[196:199], v[50:53]
	v_mfma_f32_16x16x32_bf16 v[42:45], v[160:163], v[196:199], v[42:45]
	v_mfma_f32_16x16x32_bf16 v[34:37], v[152:155], v[204:207], v[34:37]
	v_mfma_f32_16x16x32_bf16 v[26:29], v[160:163], v[204:207], v[26:29]
	v_mfma_f32_16x16x32_bf16 v[18:21], v[152:155], v[212:215], v[18:21]
	v_mfma_f32_16x16x32_bf16 v[10:13], v[160:163], v[212:215], v[10:13]
	v_mfma_f32_16x16x32_bf16 v[54:57], v[164:167], v[180:183], v[54:57]
	v_mfma_f32_16x16x32_bf16 v[46:49], v[172:175], v[180:183], v[46:49]
	v_mfma_f32_16x16x32_bf16 v[38:41], v[164:167], v[192:195], v[38:41]
	v_mfma_f32_16x16x32_bf16 v[30:33], v[172:175], v[192:195], v[30:33]
	v_mfma_f32_16x16x32_bf16 v[22:25], v[164:167], v[200:203], v[22:25]
	v_mfma_f32_16x16x32_bf16 v[14:17], v[172:175], v[200:203], v[14:17]
	v_mfma_f32_16x16x32_bf16 v[6:9], v[164:167], v[208:211], v[6:9]
	v_mfma_f32_16x16x32_bf16 v[2:5], v[172:175], v[208:211], v[2:5]
	v_mfma_f32_16x16x32_bf16 v[54:57], v[168:171], v[184:187], v[54:57]
	v_mfma_f32_16x16x32_bf16 v[46:49], v[176:179], v[184:187], v[46:49]
	v_mfma_f32_16x16x32_bf16 v[38:41], v[168:171], v[196:199], v[38:41]
	v_mfma_f32_16x16x32_bf16 v[30:33], v[176:179], v[196:199], v[30:33]
	v_mfma_f32_16x16x32_bf16 v[22:25], v[168:171], v[204:207], v[22:25]
	v_mfma_f32_16x16x32_bf16 v[14:17], v[176:179], v[204:207], v[14:17]
	v_mfma_f32_16x16x32_bf16 v[6:9], v[168:171], v[212:215], v[6:9]
	v_mfma_f32_16x16x32_bf16 v[2:5], v[176:179], v[212:215], v[2:5]
	s_setprio 0
	s_barrier
	s_add_i32 s41, s41, 2
	s_add_u32 s22, s22, 0x100
	s_addc_u32 s23, s23, 0
	s_add_u32 s39, s39, 0x100
	s_addc_u32 s40, s40, 0
	s_cmp_gt_u32 s41, 13
	s_cbranch_scc0 .LBB0_470
	v_readlane_b32 s26, v253, 27
	s_and_b64 vcc, exec, s[6:7]
	v_readlane_b32 s27, v253, 28
	s_cbranch_vccz .LBB0_473
	s_barrier

.LBB0_785:
	s_add_u32 s24, s22, 0xfffc0080
	s_addc_u32 s25, s23, -1
	s_add_i32 s43, 0, 0x10000
	s_cmp_eq_u32 s42, 12
	s_cselect_b32 s27, s11, s25
	s_cselect_b32 s26, s38, s24
	s_cselect_b32 s25, s9, s41
	s_cselect_b32 s24, s39, s40
	s_add_i32 s45, 0, 0x14000
	v_add_u32_e32 v170, s43, v200
	v_add_u32_e32 v186, s45, v200
	ds_read_b128 v[130:133], v170
	ds_read_b128 v[162:165], v170 offset:1024
	ds_read_b128 v[166:169], v170 offset:2048
	ds_read_b128 v[170:173], v170 offset:3072
	ds_read_b128 v[174:177], v186
	ds_read_b128 v[178:181], v186 offset:1024
	ds_read_b128 v[182:185], v186 offset:2048
	ds_read_b128 v[192:195], v186 offset:3072
	v_lshl_add_u64 v[186:187], s[22:23], 0, v[158:159]
	s_add_i32 m0, s19, 0xc000
	ds_read_b128 v[196:199], v202
	ds_read_b128 v[204:207], v202 offset:1024
	ds_read_b128 v[208:211], v202 offset:2048
	ds_read_b128 v[212:215], v202 offset:3072
	ds_read_b128 v[216:219], v202 offset:4096
	ds_read_b128 v[236:239], v202 offset:5120
	ds_read_b128 v[240:243], v202 offset:6144
	ds_read_b128 v[244:247], v202 offset:7168
	global_load_lds_dwordx4 v[186:187], off
	v_lshl_add_u64 v[186:187], s[22:23], 0, v[160:161]
	s_add_i32 m0, s19, 0xe000
	s_nop 0
	global_load_lds_dwordx4 v[186:187], off
	s_waitcnt vmcnt(8)
	s_waitcnt lgkmcnt(0)
	s_barrier
	s_setprio 1
	s_waitcnt lgkmcnt(0)
	v_mfma_f32_16x16x32_bf16 v[126:129], v[130:133], v[196:199], v[126:129]
	v_mfma_f32_16x16x32_bf16 v[98:101], v[166:169], v[196:199], v[98:101]
	v_mfma_f32_16x16x32_bf16 v[122:125], v[130:133], v[208:211], v[122:125]
	v_mfma_f32_16x16x32_bf16 v[90:93], v[166:169], v[208:211], v[90:93]
	v_mfma_f32_16x16x32_bf16 v[118:121], v[130:133], v[216:219], v[118:121]
	v_mfma_f32_16x16x32_bf16 v[86:89], v[166:169], v[216:219], v[86:89]
	v_mfma_f32_16x16x32_bf16 v[114:117], v[130:133], v[240:243], v[114:117]
	v_mfma_f32_16x16x32_bf16 v[82:85], v[166:169], v[240:243], v[82:85]
	v_mfma_f32_16x16x32_bf16 v[126:129], v[162:165], v[204:207], v[126:129]
	v_mfma_f32_16x16x32_bf16 v[98:101], v[170:173], v[204:207], v[98:101]
	v_mfma_f32_16x16x32_bf16 v[122:125], v[162:165], v[212:215], v[122:125]
	v_mfma_f32_16x16x32_bf16 v[90:93], v[170:173], v[212:215], v[90:93]
	v_mfma_f32_16x16x32_bf16 v[118:121], v[162:165], v[236:239], v[118:121]
	v_mfma_f32_16x16x32_bf16 v[86:89], v[170:173], v[236:239], v[86:89]
	v_mfma_f32_16x16x32_bf16 v[114:117], v[162:165], v[244:247], v[114:117]
	v_mfma_f32_16x16x32_bf16 v[82:85], v[170:173], v[244:247], v[82:85]
	v_mfma_f32_16x16x32_bf16 v[62:65], v[174:177], v[196:199], v[62:65]
	v_mfma_f32_16x16x32_bf16 v[34:37], v[182:185], v[196:199], v[34:37]
	v_mfma_f32_16x16x32_bf16 v[58:61], v[174:177], v[208:211], v[58:61]
	v_mfma_f32_16x16x32_bf16 v[26:29], v[182:185], v[208:211], v[26:29]
	v_mfma_f32_16x16x32_bf16 v[54:57], v[174:177], v[216:219], v[54:57]
	v_mfma_f32_16x16x32_bf16 v[22:25], v[182:185], v[216:219], v[22:25]
	v_mfma_f32_16x16x32_bf16 v[50:53], v[174:177], v[240:243], v[50:53]
	v_mfma_f32_16x16x32_bf16 v[18:21], v[182:185], v[240:243], v[18:21]
	v_mfma_f32_16x16x32_bf16 v[62:65], v[178:181], v[204:207], v[62:65]
	v_mfma_f32_16x16x32_bf16 v[34:37], v[192:195], v[204:207], v[34:37]
	v_mfma_f32_16x16x32_bf16 v[58:61], v[178:181], v[212:215], v[58:61]
	v_mfma_f32_16x16x32_bf16 v[26:29], v[192:195], v[212:215], v[26:29]
	v_mfma_f32_16x16x32_bf16 v[54:57], v[178:181], v[236:239], v[54:57]
	v_mfma_f32_16x16x32_bf16 v[22:25], v[192:195], v[236:239], v[22:25]
	v_mfma_f32_16x16x32_bf16 v[50:53], v[178:181], v[244:247], v[50:53]
	v_mfma_f32_16x16x32_bf16 v[18:21], v[192:195], v[244:247], v[18:21]
	s_setprio 0
	s_barrier
	s_add_i32 s43, s43, s18
	v_lshl_add_u64 v[186:187], s[24:25], 0, v[138:139]
	s_mov_b32 m0, s43
	ds_read_b128 v[196:199], v202 offset:16384
	ds_read_b128 v[204:207], v202 offset:17408
	ds_read_b128 v[208:211], v202 offset:18432
	ds_read_b128 v[212:215], v202 offset:19456
	ds_read_b128 v[216:219], v202 offset:20480
	ds_read_b128 v[236:239], v202 offset:21504
	ds_read_b128 v[240:243], v202 offset:22528
	ds_read_b128 v[244:247], v202 offset:23552
	global_load_lds_dwordx4 v[186:187], off
	s_add_i32 m0, s43, 0x2000
	s_add_u32 s62, s24, 0x40000
	v_lshl_add_u64 v[220:221], s[24:25], 0, v[134:135]
	s_addc_u32 s63, s25, 0
	s_add_i32 s43, s45, s18
	global_load_lds_dwordx4 v[220:221], off
	v_lshl_add_u64 v[248:249], s[62:63], 0, v[138:139]
	s_mov_b32 m0, s43
	v_lshl_add_u64 v[250:251], s[26:27], 0, v[136:137]
	global_load_lds_dwordx4 v[248:249], off
	v_lshl_add_u64 v[248:249], s[62:63], 0, v[134:135]
	s_add_i32 m0, s43, 0x2000
	s_nop 0
	global_load_lds_dwordx4 v[248:249], off
	v_lshl_add_u64 v[248:249], s[26:27], 0, v[140:141]
	s_mov_b32 m0, s19
	s_nop 0
	global_load_lds_dwordx4 v[248:249], off
	s_mov_b32 m0, s28
	s_nop 0
	global_load_lds_dwordx4 v[250:251], off
	s_waitcnt vmcnt(8)
	s_waitcnt lgkmcnt(0)
	s_barrier
	s_setprio 1
	s_waitcnt lgkmcnt(0)
	v_mfma_f32_16x16x32_bf16 v[110:113], v[130:133], v[196:199], v[110:113]
	v_mfma_f32_16x16x32_bf16 v[78:81], v[166:169], v[196:199], v[78:81]
	v_mfma_f32_16x16x32_bf16 v[106:109], v[130:133], v[208:211], v[106:109]
	v_mfma_f32_16x16x32_bf16 v[74:77], v[166:169], v[208:211], v[74:77]
	v_mfma_f32_16x16x32_bf16 v[102:105], v[130:133], v[216:219], v[102:105]
	v_mfma_f32_16x16x32_bf16 v[70:73], v[166:169], v[216:219], v[70:73]
	v_mfma_f32_16x16x32_bf16 v[94:97], v[130:133], v[240:243], v[94:97]
	v_mfma_f32_16x16x32_bf16 v[66:69], v[166:169], v[240:243], v[66:69]
	v_mfma_f32_16x16x32_bf16 v[110:113], v[162:165], v[204:207], v[110:113]
	v_mfma_f32_16x16x32_bf16 v[78:81], v[170:173], v[204:207], v[78:81]
	v_mfma_f32_16x16x32_bf16 v[106:109], v[162:165], v[212:215], v[106:109]
	v_mfma_f32_16x16x32_bf16 v[74:77], v[170:173], v[212:215], v[74:77]
	v_mfma_f32_16x16x32_bf16 v[102:105], v[162:165], v[236:239], v[102:105]
	v_mfma_f32_16x16x32_bf16 v[70:73], v[170:173], v[236:239], v[70:73]
	v_mfma_f32_16x16x32_bf16 v[94:97], v[162:165], v[244:247], v[94:97]
	v_mfma_f32_16x16x32_bf16 v[66:69], v[170:173], v[244:247], v[66:69]
	v_mfma_f32_16x16x32_bf16 v[46:49], v[174:177], v[196:199], v[46:49]
	v_mfma_f32_16x16x32_bf16 v[14:17], v[182:185], v[196:199], v[14:17]
	v_mfma_f32_16x16x32_bf16 v[42:45], v[174:177], v[208:211], v[42:45]
	v_mfma_f32_16x16x32_bf16 v[10:13], v[182:185], v[208:211], v[10:13]
	v_mfma_f32_16x16x32_bf16 v[38:41], v[174:177], v[216:219], v[38:41]
	v_mfma_f32_16x16x32_bf16 v[6:9], v[182:185], v[216:219], v[6:9]
	v_mfma_f32_16x16x32_bf16 v[30:33], v[174:177], v[240:243], v[30:33]
	v_mfma_f32_16x16x32_bf16 v[2:5], v[182:185], v[240:243], v[2:5]
	v_mfma_f32_16x16x32_bf16 v[46:49], v[178:181], v[204:207], v[46:49]
	v_mfma_f32_16x16x32_bf16 v[14:17], v[192:195], v[204:207], v[14:17]
	v_mfma_f32_16x16x32_bf16 v[42:45], v[178:181], v[212:215], v[42:45]
	v_mfma_f32_16x16x32_bf16 v[10:13], v[192:195], v[212:215], v[10:13]
	v_mfma_f32_16x16x32_bf16 v[38:41], v[178:181], v[236:239], v[38:41]
	v_mfma_f32_16x16x32_bf16 v[6:9], v[192:195], v[236:239], v[6:9]
	v_mfma_f32_16x16x32_bf16 v[30:33], v[178:181], v[244:247], v[30:33]
	v_mfma_f32_16x16x32_bf16 v[2:5], v[192:195], v[244:247], v[2:5]
	s_setprio 0
	s_barrier
	s_add_i32 s43, 0, 0x18000
	s_add_i32 s45, 0, 0x1c000
	v_add_u32_e32 v170, s43, v200
	v_add_u32_e32 v192, s45, v200
	ds_read_b128 v[130:133], v170
	ds_read_b128 v[162:165], v170 offset:1024
	ds_read_b128 v[166:169], v170 offset:2048
	ds_read_b128 v[170:173], v170 offset:3072
	ds_read_b128 v[174:177], v192
	ds_read_b128 v[178:181], v192 offset:1024
	ds_read_b128 v[182:185], v192 offset:2048
	ds_read_b128 v[192:195], v192 offset:3072
	s_add_u32 s26, s26, 0x40000
	s_addc_u32 s27, s27, 0
	s_mov_b32 m0, s29
	v_lshl_add_u64 v[230:231], s[26:27], 0, v[140:141]
	ds_read_b128 v[196:199], v202 offset:32768
	ds_read_b128 v[204:207], v202 offset:33792
	ds_read_b128 v[208:211], v202 offset:34816
	ds_read_b128 v[212:215], v202 offset:35840
	ds_read_b128 v[216:219], v202 offset:36864
	ds_read_b128 v[236:239], v202 offset:37888
	ds_read_b128 v[240:243], v202 offset:38912
	ds_read_b128 v[244:247], v202 offset:39936
	global_load_lds_dwordx4 v[230:231], off
	v_lshl_add_u64 v[230:231], s[26:27], 0, v[136:137]
	s_mov_b32 m0, s30
	s_nop 0
	global_load_lds_dwordx4 v[230:231], off
	s_waitcnt vmcnt(8)
	s_waitcnt lgkmcnt(0)
	s_barrier
	s_setprio 1
	s_waitcnt lgkmcnt(0)
	v_mfma_f32_16x16x32_bf16 v[126:129], v[130:133], v[196:199], v[126:129]
	v_mfma_f32_16x16x32_bf16 v[98:101], v[166:169], v[196:199], v[98:101]
	v_mfma_f32_16x16x32_bf16 v[122:125], v[130:133], v[208:211], v[122:125]
	v_mfma_f32_16x16x32_bf16 v[90:93], v[166:169], v[208:211], v[90:93]
	v_mfma_f32_16x16x32_bf16 v[118:121], v[130:133], v[216:219], v[118:121]
	v_mfma_f32_16x16x32_bf16 v[86:89], v[166:169], v[216:219], v[86:89]
	v_mfma_f32_16x16x32_bf16 v[114:117], v[130:133], v[240:243], v[114:117]
	v_mfma_f32_16x16x32_bf16 v[82:85], v[166:169], v[240:243], v[82:85]
	v_mfma_f32_16x16x32_bf16 v[126:129], v[162:165], v[204:207], v[126:129]
	v_mfma_f32_16x16x32_bf16 v[98:101], v[170:173], v[204:207], v[98:101]
	v_mfma_f32_16x16x32_bf16 v[122:125], v[162:165], v[212:215], v[122:125]
	v_mfma_f32_16x16x32_bf16 v[90:93], v[170:173], v[212:215], v[90:93]
	v_mfma_f32_16x16x32_bf16 v[118:121], v[162:165], v[236:239], v[118:121]
	v_mfma_f32_16x16x32_bf16 v[86:89], v[170:173], v[236:239], v[86:89]
	v_mfma_f32_16x16x32_bf16 v[114:117], v[162:165], v[244:247], v[114:117]
	v_mfma_f32_16x16x32_bf16 v[82:85], v[170:173], v[244:247], v[82:85]
	v_mfma_f32_16x16x32_bf16 v[62:65], v[174:177], v[196:199], v[62:65]
	v_mfma_f32_16x16x32_bf16 v[34:37], v[182:185], v[196:199], v[34:37]
	v_mfma_f32_16x16x32_bf16 v[58:61], v[174:177], v[208:211], v[58:61]
	v_mfma_f32_16x16x32_bf16 v[26:29], v[182:185], v[208:211], v[26:29]
	v_mfma_f32_16x16x32_bf16 v[54:57], v[174:177], v[216:219], v[54:57]
	v_mfma_f32_16x16x32_bf16 v[22:25], v[182:185], v[216:219], v[22:25]
	v_mfma_f32_16x16x32_bf16 v[50:53], v[174:177], v[240:243], v[50:53]
	v_mfma_f32_16x16x32_bf16 v[18:21], v[182:185], v[240:243], v[18:21]
	v_mfma_f32_16x16x32_bf16 v[62:65], v[178:181], v[204:207], v[62:65]
	v_mfma_f32_16x16x32_bf16 v[34:37], v[192:195], v[204:207], v[34:37]
	v_mfma_f32_16x16x32_bf16 v[58:61], v[178:181], v[212:215], v[58:61]
	v_mfma_f32_16x16x32_bf16 v[26:29], v[192:195], v[212:215], v[26:29]
	v_mfma_f32_16x16x32_bf16 v[54:57], v[178:181], v[236:239], v[54:57]
	v_mfma_f32_16x16x32_bf16 v[22:25], v[192:195], v[236:239], v[22:25]
	v_mfma_f32_16x16x32_bf16 v[50:53], v[178:181], v[244:247], v[50:53]
	v_mfma_f32_16x16x32_bf16 v[18:21], v[192:195], v[244:247], v[18:21]
	s_setprio 0
	s_barrier
	s_add_i32 s26, s43, s18
	v_lshl_add_u64 v[186:187], v[186:187], 0, s[94:95]
	s_mov_b32 m0, s26
	ds_read_b128 v[196:199], v202 offset:49152
	ds_read_b128 v[204:207], v202 offset:50176
	ds_read_b128 v[208:211], v202 offset:51200
	ds_read_b128 v[212:215], v202 offset:52224
	ds_read_b128 v[216:219], v202 offset:53248
	ds_read_b128 v[236:239], v202 offset:54272
	ds_read_b128 v[240:243], v202 offset:55296
	ds_read_b128 v[244:247], v202 offset:56320
	global_load_lds_dwordx4 v[186:187], off
	s_add_i32 m0, s26, 0x2000
	s_add_u32 s24, s24, 0x40080
	v_lshl_add_u64 v[186:187], v[220:221], 0, s[94:95]
	s_addc_u32 s25, s25, 0
	s_add_i32 s26, s45, s18
	global_load_lds_dwordx4 v[186:187], off
	v_lshl_add_u64 v[186:187], s[24:25], 0, v[138:139]
	s_mov_b32 m0, s26
	s_nop 0
	global_load_lds_dwordx4 v[186:187], off
	v_lshl_add_u64 v[186:187], s[24:25], 0, v[134:135]
	s_add_i32 m0, s26, 0x2000
	s_nop 0
	global_load_lds_dwordx4 v[186:187], off
	v_lshl_add_u64 v[186:187], v[248:249], 0, s[94:95]
	s_mov_b32 m0, s31
	s_nop 0
	global_load_lds_dwordx4 v[186:187], off
	v_lshl_add_u64 v[186:187], v[250:251], 0, s[94:95]
	s_mov_b32 m0, s34
	s_nop 0
	global_load_lds_dwordx4 v[186:187], off
	s_waitcnt vmcnt(8)
	s_waitcnt lgkmcnt(0)
	s_barrier
	s_setprio 1
	s_waitcnt lgkmcnt(0)
	v_mfma_f32_16x16x32_bf16 v[110:113], v[130:133], v[196:199], v[110:113]
	v_mfma_f32_16x16x32_bf16 v[78:81], v[166:169], v[196:199], v[78:81]
	v_mfma_f32_16x16x32_bf16 v[106:109], v[130:133], v[208:211], v[106:109]
	v_mfma_f32_16x16x32_bf16 v[74:77], v[166:169], v[208:211], v[74:77]
	v_mfma_f32_16x16x32_bf16 v[102:105], v[130:133], v[216:219], v[102:105]
	v_mfma_f32_16x16x32_bf16 v[70:73], v[166:169], v[216:219], v[70:73]
	v_mfma_f32_16x16x32_bf16 v[94:97], v[130:133], v[240:243], v[94:97]
	v_mfma_f32_16x16x32_bf16 v[66:69], v[166:169], v[240:243], v[66:69]
	v_mfma_f32_16x16x32_bf16 v[110:113], v[162:165], v[204:207], v[110:113]
	v_mfma_f32_16x16x32_bf16 v[78:81], v[170:173], v[204:207], v[78:81]
	v_mfma_f32_16x16x32_bf16 v[106:109], v[162:165], v[212:215], v[106:109]
	v_mfma_f32_16x16x32_bf16 v[74:77], v[170:173], v[212:215], v[74:77]
	v_mfma_f32_16x16x32_bf16 v[102:105], v[162:165], v[236:239], v[102:105]
	v_mfma_f32_16x16x32_bf16 v[70:73], v[170:173], v[236:239], v[70:73]
	v_mfma_f32_16x16x32_bf16 v[94:97], v[162:165], v[244:247], v[94:97]
	v_mfma_f32_16x16x32_bf16 v[66:69], v[170:173], v[244:247], v[66:69]
	v_mfma_f32_16x16x32_bf16 v[46:49], v[174:177], v[196:199], v[46:49]
	v_mfma_f32_16x16x32_bf16 v[14:17], v[182:185], v[196:199], v[14:17]
	v_mfma_f32_16x16x32_bf16 v[42:45], v[174:177], v[208:211], v[42:45]
	v_mfma_f32_16x16x32_bf16 v[10:13], v[182:185], v[208:211], v[10:13]
	v_mfma_f32_16x16x32_bf16 v[38:41], v[174:177], v[216:219], v[38:41]
	v_mfma_f32_16x16x32_bf16 v[6:9], v[182:185], v[216:219], v[6:9]
	v_mfma_f32_16x16x32_bf16 v[30:33], v[174:177], v[240:243], v[30:33]
	v_mfma_f32_16x16x32_bf16 v[2:5], v[182:185], v[240:243], v[2:5]
	v_mfma_f32_16x16x32_bf16 v[46:49], v[178:181], v[204:207], v[46:49]
	v_mfma_f32_16x16x32_bf16 v[14:17], v[192:195], v[204:207], v[14:17]
	v_mfma_f32_16x16x32_bf16 v[42:45], v[178:181], v[212:215], v[42:45]
	v_mfma_f32_16x16x32_bf16 v[10:13], v[192:195], v[212:215], v[10:13]
	v_mfma_f32_16x16x32_bf16 v[38:41], v[178:181], v[236:239], v[38:41]
	v_mfma_f32_16x16x32_bf16 v[6:9], v[192:195], v[236:239], v[6:9]
	v_mfma_f32_16x16x32_bf16 v[30:33], v[178:181], v[244:247], v[30:33]
	v_mfma_f32_16x16x32_bf16 v[2:5], v[192:195], v[244:247], v[2:5]
	s_setprio 0
	s_barrier
	s_add_i32 s42, s42, 2
	s_add_u32 s22, s22, 0x100
	s_addc_u32 s23, s23, 0
	s_add_u32 s40, s40, 0x100
	s_addc_u32 s41, s41, 0
	s_cmp_gt_u32 s42, 13
	s_cbranch_scc0 .LBB0_785
	s_and_b64 vcc, exec, s[6:7]
	s_cbranch_vccz .LBB0_788
	s_barrier
